# diff tile loop stagger: waves 4-7 (the SIMD partners of waves 0-3) sleep 256 cycles after each tile barrier so the two waves of a SIMD stop running their MFMA and softmax sections in lockstep
# speedup vs baseline: 1.0069x; 1.0068x over previous
.LBB0_472:
	s_or_b64 exec, exec, s[0:1]
	s_waitcnt vmcnt(5)
	v_lshlrev_b32_e32 v35, 16, v30
	v_and_b32_e32 v30, 0xffff0000, v30
	v_mul_f32_e32 v30, 0x3e38aa3b, v30
	v_mul_f32_e32 v35, 0x3e38aa3b, v35
	v_cvt_pk_bf16_f32 v98, v35, v30
	v_lshlrev_b32_e32 v30, 16, v31
	v_mul_f32_e32 v30, 0x3e38aa3b, v30
	v_and_b32_e32 v31, 0xffff0000, v31
	v_mul_f32_e32 v31, 0x3e38aa3b, v31
	v_cvt_pk_bf16_f32 v99, v30, v31
	v_lshlrev_b32_e32 v30, 16, v32
	v_mul_f32_e32 v30, 0x3e38aa3b, v30
	v_and_b32_e32 v31, 0xffff0000, v32
	v_mul_f32_e32 v31, 0x3e38aa3b, v31
	v_cvt_pk_bf16_f32 v100, v30, v31
	v_lshlrev_b32_e32 v30, 16, v33
	v_mul_f32_e32 v30, 0x3e38aa3b, v30
	v_and_b32_e32 v31, 0xffff0000, v33
	v_mul_f32_e32 v31, 0x3e38aa3b, v31
	v_cvt_pk_bf16_f32 v101, v30, v31
	s_waitcnt vmcnt(3)
	v_lshlrev_b32_e32 v30, 16, v26
	v_and_b32_e32 v26, 0xffff0000, v26
	v_mul_f32_e32 v26, 0x3e38aa3b, v26
	v_mul_f32_e32 v30, 0x3e38aa3b, v30
	v_cvt_pk_bf16_f32 v102, v30, v26
	v_lshlrev_b32_e32 v26, 16, v27
	v_mul_f32_e32 v26, 0x3e38aa3b, v26
	v_and_b32_e32 v27, 0xffff0000, v27
	v_mul_f32_e32 v27, 0x3e38aa3b, v27
	v_cvt_pk_bf16_f32 v103, v26, v27
	v_lshlrev_b32_e32 v26, 16, v28
	v_mul_f32_e32 v26, 0x3e38aa3b, v26
	v_and_b32_e32 v27, 0xffff0000, v28
	v_mul_f32_e32 v27, 0x3e38aa3b, v27
	v_cvt_pk_bf16_f32 v104, v26, v27
	v_lshlrev_b32_e32 v26, 16, v29
	v_mul_f32_e32 v26, 0x3e38aa3b, v26
	v_and_b32_e32 v27, 0xffff0000, v29
	v_mul_f32_e32 v27, 0x3e38aa3b, v27
	v_cvt_pk_bf16_f32 v105, v26, v27
	v_lshlrev_b32_e32 v26, 16, v22
	v_and_b32_e32 v22, 0xffff0000, v22
	v_mul_f32_e32 v22, 0x3e38aa3b, v22
	v_mul_f32_e32 v26, 0x3e38aa3b, v26
	v_cvt_pk_bf16_f32 v106, v26, v22
	v_lshlrev_b32_e32 v22, 16, v23
	v_mul_f32_e32 v22, 0x3e38aa3b, v22
	v_and_b32_e32 v23, 0xffff0000, v23
	v_mul_f32_e32 v23, 0x3e38aa3b, v23
	v_cvt_pk_bf16_f32 v107, v22, v23
	v_lshlrev_b32_e32 v22, 16, v24
	v_mul_f32_e32 v22, 0x3e38aa3b, v22
	v_and_b32_e32 v23, 0xffff0000, v24
	v_mul_f32_e32 v23, 0x3e38aa3b, v23
	v_cvt_pk_bf16_f32 v108, v22, v23
	v_lshlrev_b32_e32 v22, 16, v25
	v_mul_f32_e32 v22, 0x3e38aa3b, v22
	v_and_b32_e32 v23, 0xffff0000, v25
	v_mul_f32_e32 v23, 0x3e38aa3b, v23
	v_cvt_pk_bf16_f32 v109, v22, v23
	v_lshlrev_b32_e32 v22, 16, v14
	v_and_b32_e32 v14, 0xffff0000, v14
	v_mul_f32_e32 v14, 0x3e38aa3b, v14
	v_mul_f32_e32 v22, 0x3e38aa3b, v22
	v_cvt_pk_bf16_f32 v110, v22, v14
	v_lshlrev_b32_e32 v14, 16, v15
	v_mul_f32_e32 v14, 0x3e38aa3b, v14
	v_and_b32_e32 v15, 0xffff0000, v15
	v_mul_f32_e32 v15, 0x3e38aa3b, v15
	v_cvt_pk_bf16_f32 v111, v14, v15
	v_lshlrev_b32_e32 v14, 16, v16
	v_mul_f32_e32 v14, 0x3e38aa3b, v14
	v_and_b32_e32 v15, 0xffff0000, v16
	v_mul_f32_e32 v15, 0x3e38aa3b, v15
	v_cvt_pk_bf16_f32 v112, v14, v15
	v_lshlrev_b32_e32 v14, 16, v17
	v_mul_f32_e32 v14, 0x3e38aa3b, v14
	v_and_b32_e32 v15, 0xffff0000, v17
	s_movk_i32 s0, 0x110
	v_mul_f32_e32 v15, 0x3e38aa3b, v15
	v_cvt_pk_bf16_f32 v113, v14, v15
	v_mul_lo_u32 v14, v37, s0
	v_lshl_add_u32 v151, v38, 4, v14
	s_movk_i32 s0, 0x90
	v_mul_lo_u32 v14, v36, s0
	v_lshlrev_b32_e32 v16, 3, v134
	v_add_u32_e32 v17, 0, v151
	v_and_b32_e32 v15, 0x60, v34
	ds_write_b128 v17, v[6:9]
	s_waitcnt vmcnt(1)
	ds_write_b128 v17, v[18:21] offset:8704
	v_and_or_b32 v6, v16, 8, v14
	v_add_u32_e32 v152, v6, v15
	v_add_u32_e32 v6, 0, v152
	v_add_u32_e32 v7, 0x4000, v6
	ds_write2_b64 v7, v[2:3], v[4:5] offset0:128 offset1:130
	v_add_u32_e32 v2, 0x6800, v6
	v_readlane_b32 s0, v253, 49
	s_waitcnt vmcnt(0)
	ds_write2_b64 v2, v[10:11], v[12:13] offset1:2
	s_waitcnt lgkmcnt(0)
	v_mov_b32_e32 v2, s0
	s_barrier
	ds_read_b32 v149, v2
	v_mov_b32_e32 v137, 1.0
	v_mov_b32_e32 v17, 0
	s_cmp_lt_i32 s2, 0
	v_mov_b32_e32 v16, 0
	v_mov_b32_e32 v15, 0
	v_mov_b32_e32 v14, 0
	v_mov_b32_e32 v13, 0
	v_mov_b32_e32 v12, 0
	v_mov_b32_e32 v11, 0
	v_mov_b32_e32 v10, 0
	v_mov_b32_e32 v9, 0
	v_mov_b32_e32 v8, 0
	v_mov_b32_e32 v7, 0
	v_mov_b32_e32 v6, 0
	v_mov_b32_e32 v5, 0
	v_mov_b32_e32 v4, 0
	v_mov_b32_e32 v3, 0
	v_mov_b32_e32 v2, 0
	v_mov_b32_e32 v33, 0
	v_mov_b32_e32 v32, 0
	v_mov_b32_e32 v31, 0
	v_mov_b32_e32 v30, 0
	v_mov_b32_e32 v29, 0
	v_mov_b32_e32 v28, 0
	v_mov_b32_e32 v27, 0
	v_mov_b32_e32 v26, 0
	v_mov_b32_e32 v25, 0
	v_mov_b32_e32 v24, 0
	v_mov_b32_e32 v23, 0
	v_mov_b32_e32 v22, 0
	v_mov_b32_e32 v21, 0
	v_mov_b32_e32 v20, 0
	v_mov_b32_e32 v19, 0
	v_mov_b32_e32 v18, 0
	v_mov_b32_e32 v49, 0
	v_mov_b32_e32 v48, 0
	v_mov_b32_e32 v47, 0
	v_mov_b32_e32 v46, 0
	v_mov_b32_e32 v45, 0
	v_mov_b32_e32 v44, 0
	v_mov_b32_e32 v43, 0
	v_mov_b32_e32 v42, 0
	v_mov_b32_e32 v41, 0
	v_mov_b32_e32 v40, 0
	v_mov_b32_e32 v39, 0
	v_mov_b32_e32 v38, 0
	v_mov_b32_e32 v37, 0
	v_mov_b32_e32 v36, 0
	v_mov_b32_e32 v35, 0
	v_mov_b32_e32 v34, 0
	v_mov_b32_e32 v65, 0
	v_mov_b32_e32 v64, 0
	v_mov_b32_e32 v63, 0
	v_mov_b32_e32 v62, 0
	v_mov_b32_e32 v61, 0
	v_mov_b32_e32 v60, 0
	v_mov_b32_e32 v59, 0
	v_mov_b32_e32 v58, 0
	v_mov_b32_e32 v57, 0
	v_mov_b32_e32 v56, 0
	v_mov_b32_e32 v55, 0
	v_mov_b32_e32 v54, 0
	v_mov_b32_e32 v53, 0
	v_mov_b32_e32 v52, 0
	v_mov_b32_e32 v51, 0
	v_mov_b32_e32 v50, 0
	v_mov_b32_e32 v131, 0
	s_cbranch_scc1 .LBB0_492
	s_movk_i32 s0, 0x1c00
	v_mad_i64_i32 v[2:3], s[0:1], v70, s0, 0
	v_lshl_add_u64 v[2:3], v[2:3], 0, v[0:1]
	v_mov_b32_e32 v14, v1
	v_mov_b32_e32 v15, v1
	s_mov_b64 s[0:1], 0x1800
	v_lshl_add_u64 v[144:145], s[42:43], 0, v[2:3]
	v_mov_b32_e32 v0, v1
	v_mov_b32_e32 v2, v1
	v_mov_b32_e32 v3, v1
	v_mov_b32_e32 v4, v1
	v_mov_b32_e32 v5, v1
	v_mov_b32_e32 v6, v1
	v_mov_b32_e32 v7, v1
	v_mov_b32_e32 v8, v1
	v_mov_b32_e32 v9, v1
	v_mov_b32_e32 v10, v1
	v_mov_b32_e32 v11, v1
	v_mov_b32_e32 v12, v1
	v_mov_b32_e32 v13, v1
	v_mov_b64_e32 v[64:65], v[14:15]
	v_mov_b64_e32 v[48:49], v[14:15]
	v_mov_b64_e32 v[32:33], v[14:15]
	v_lshl_add_u64 v[140:141], v[66:67], 0, s[0:1]
	s_mov_b64 s[0:1], 0x200000
	s_lshl_b32 s2, s2, 1
	v_ashrrev_i32_e32 v155, 8, v134
	v_subrev_u32_e32 v156, 63, v69
	v_mov_b64_e32 v[62:63], v[12:13]
	v_mov_b64_e32 v[60:61], v[10:11]
	v_mov_b64_e32 v[58:59], v[8:9]
	v_mov_b64_e32 v[56:57], v[6:7]
	v_mov_b64_e32 v[54:55], v[4:5]
	v_mov_b64_e32 v[52:53], v[2:3]
	v_mov_b64_e32 v[50:51], v[0:1]
	v_mov_b64_e32 v[46:47], v[12:13]
	v_mov_b64_e32 v[44:45], v[10:11]
	v_mov_b64_e32 v[42:43], v[8:9]
	v_mov_b64_e32 v[40:41], v[6:7]
	v_mov_b64_e32 v[38:39], v[4:5]
	v_mov_b64_e32 v[36:37], v[2:3]
	v_mov_b64_e32 v[34:35], v[0:1]
	v_mov_b64_e32 v[30:31], v[12:13]
	v_mov_b64_e32 v[28:29], v[10:11]
	v_mov_b64_e32 v[26:27], v[8:9]
	v_mov_b64_e32 v[24:25], v[6:7]
	v_mov_b64_e32 v[22:23], v[4:5]
	v_mov_b64_e32 v[20:21], v[2:3]
	v_mov_b64_e32 v[18:19], v[0:1]
	v_mov_b64_e32 v[16:17], v[14:15]
	v_lshl_add_u64 v[142:143], v[138:139], 0, s[0:1]
	v_add_u32_e32 v157, s2, v155
	v_mul_u32_u24_e32 v154, 0x110, v68
	v_mul_i32_i24_e32 v153, -4, v135
	v_mul_u32_u24_e32 v133, 0x90, v68
	v_mad_i32_i24 v158, v135, -4, v68
	s_or_b32 s3, s2, 1
	s_mov_b32 s4, 0
	v_mov_b32_e32 v150, 0xff800000
	v_mov_b32_e32 v131, 0
	s_mov_b32 s52, 64
	v_mov_b32_e32 v159, v156
	v_mov_b64_e32 v[14:15], v[12:13]
	v_mov_b64_e32 v[12:13], v[10:11]
	v_mov_b64_e32 v[10:11], v[8:9]
	v_mov_b64_e32 v[8:9], v[6:7]
	v_mov_b64_e32 v[6:7], v[4:5]
	v_mov_b64_e32 v[4:5], v[2:3]
	v_mov_b64_e32 v[2:3], v[0:1]
	v_readfirstlane_b32 s99, v147
	s_branch .LBB0_475

.LBB0_475:
	s_cmp_lt_u32 s99, 2
	s_cbranch_scc1 .Ldf_nosleep
	s_sleep 4
